# kv_unit: 16x8B sc1 stores merged into 8x16B sc1 stores
# speedup vs baseline: 1.0059x; 1.0059x over previous
; #define LAS __attribute__((address_space(3)))
; __device__ __forceinline__ unsigned pk2(float lo, float hi) { return pg8::cvt_pk_bf16(lo, hi); }
; __device__ __forceinline__ float fexp2(float x) { return __builtin_amdgcn_exp2f(x); }
; __device__ __forceinline__ float ret_log2gamma(int h) { return log2f(1.f - exp2f(-5.f - (float)h)); }
; template <bool SC> __device__ __forceinline__ void stage_tr(LAS bfu* dst, const bfu* src, int pitch, int tid, float lg) {
; #pragma unroll
;     for (int i = 0; i < 4; ++i) { const int id = tid + NTHR * i, c = id & 127, ch = id >> 7; const v4u v = *(const v4u*)(src + (size_t)c * pitch + ch * 8);
;         const float sc = SC ? fexp2(lg * (float)(127 - c)) : 1.f;
; #pragma unroll
;         for (int j = 0; j < 4; ++j) { unsigned w = v[j];
;             if (SC) w = pk2(bflo(w) * sc, bfhi(w) * sc);
;             dst[(ch * 8 + 2 * j) * TS + c] = (bfu)(w & 0xffffu); dst[(ch * 8 + 2 * j + 1) * TS + c] = (bfu)(w >> 16); } }
; }
; __device__ __forceinline__ void kv_unit(LAS unsigned char* lds, const bfu* PROJ, float* KVT, int u) {
;     ...
;     const int bh = u >> 6, i = u & 63, b = bh / 6, h = bh % 6; const size_t row0 = (size_t)b * SEQ + (size_t)i * 128; const float lg = ret_log2gamma(h);
;     LAS bfu* Vt = (LAS bfu*)lds; LAS bfu* Kt = (LAS bfu*)(lds + TILE_B);
;     stage_tr<false>(Vt, PROJ + row0 * INW + C_RV + h * 128, INW, tid, 0.f);
;     stage_tr<true>(Kt, PROJ + row0 * INW + C_RK + h * 128, INW, tid, lg);
.LBB0_272:
	s_mov_b32 s22, 21
	s_ashr_i32 s23, s22, 31
	s_lshl_b64 s[22:23], s[22:23], 3
	s_add_u32 s22, s0, s22
	s_addc_u32 s23, s1, s23
	s_load_dwordx2 s[34:35], s[22:23], 0x0
	s_mov_b32 s22, 21
	s_ashr_i32 s23, s22, 31
	s_lshl_b64 s[22:23], s[22:23], 3
	s_add_u32 s22, s0, s22
	s_addc_u32 s23, s1, s23
	s_ashr_i32 s44, s40, 6
	s_load_dwordx2 s[46:47], s[22:23], 0x0
	s_mul_hi_i32 s22, s44, 0x2aaaaaab
	s_lshr_b32 s23, s22, 31
	s_add_i32 s22, s22, s23
	s_mul_i32 s23, s22, 6
	s_sub_i32 s41, s44, s23
	v_cvt_f32_i32_e32 v0, s41
	s_ashr_i32 s23, s22, 31
	s_lshl_b32 s45, s40, 7
	s_lshl_b64 s[22:23], s[22:23], 13
	v_sub_f32_e32 v0, 0xc0a00000, v0
	v_cmp_gt_f32_e32 vcc, s64, v0
	s_and_b32 s45, s45, 0x1f80
	s_or_b32 s22, s22, s45
	v_cndmask_b32_e32 v2, 0, v241, vcc
	v_add_f32_e32 v0, v0, v2
	v_exp_f32_e32 v0, v0
	s_and_b64 s[48:49], vcc, exec
	s_cselect_b32 s45, 0xffffffc0, 0
	s_mulk_i32 s23, 0x3200
	v_ldexp_f32 v0, v0, s45
	v_sub_f32_e32 v0, 1.0, v0
	v_cmp_gt_f32_e32 vcc, s52, v0
	s_and_b64 s[48:49], vcc, exec
	s_cselect_b32 s45, 32, 0
	v_ldexp_f32 v0, v0, s45
	s_mul_hi_u32 s45, s22, 0x3200
	s_add_i32 s45, s45, s23
	s_mulk_i32 s22, 0x3200
	v_log_f32_e32 v0, v0
	s_waitcnt lgkmcnt(0)
	s_add_u32 s34, s34, s22
	s_addc_u32 s35, s35, s45
	s_lshl_b32 s22, s41, 7
	v_mov_b32_e32 v8, v232
	s_ashr_i32 s23, s22, 31
	v_cndmask_b32_e32 v2, 0, v242, vcc
	s_lshl_b64 s[22:23], s[22:23], 1
	v_and_b32_e32 v4, 0x7f, v8
	v_sub_f32_e32 v17, v0, v2
	s_add_u32 s22, s34, s22
	v_mul_u32_u24_e32 v0, 0x1900, v4
	s_addc_u32 s23, s35, s23
	v_lshlrev_b32_e32 v0, 1, v0
	v_lshl_add_u64 v[2:3], s[22:23], 0, v[0:1]
	s_mov_b64 s[22:23], 0x1ce00000
	v_ashrrev_i32_e32 v0, 4, v8
	v_lshl_add_u64 v[14:15], v[2:3], 0, s[22:23]
	v_and_b32_e32 v2, -8, v0
	v_ashrrev_i32_e32 v3, 31, v2
	v_lshl_add_u64 v[18:19], v[2:3], 1, v[14:15]
	v_mul_lo_u32 v0, v2, s65
	v_lshlrev_b32_e32 v9, 1, v4
	global_load_dwordx4 v[2:5], v[18:19], off offset:3072
	v_add3_u32 v20, 0, v0, v9
	v_add_u32_e32 v0, 0x200, v8
	v_ashrrev_i32_e32 v0, 4, v0
	s_movk_i32 s22, 0x7f
	v_readfirstlane_b32 s20, v8
	s_ashr_i32 s20, s20, 2
	s_ashr_i32 s41, s40, 31
	s_waitcnt vmcnt(0)
	ds_write_b16 v20, v2
	ds_write_b16_d16_hi v20, v2 offset:272
	ds_write_b16 v20, v3 offset:544
	ds_write_b16_d16_hi v20, v3 offset:816
	ds_write_b16 v20, v4 offset:1088
	ds_write_b16_d16_hi v20, v4 offset:1360
	ds_write_b16 v20, v5 offset:1632
	ds_write_b16_d16_hi v20, v5 offset:1904
	v_and_b32_e32 v2, -8, v0
	v_ashrrev_i32_e32 v3, 31, v2
	v_lshl_add_u64 v[6:7], v[2:3], 1, v[14:15]
	v_mul_lo_u32 v0, v2, s65
	global_load_dwordx4 v[2:5], v[6:7], off offset:3072
	v_add3_u32 v21, 0, v0, v9
	v_add_u32_e32 v0, 0x400, v8
	v_ashrrev_i32_e32 v0, 4, v0
	s_waitcnt vmcnt(0)
	ds_write_b16 v21, v2
	ds_write_b16_d16_hi v21, v2 offset:272
	ds_write_b16 v21, v3 offset:544
	ds_write_b16_d16_hi v21, v3 offset:816
	ds_write_b16 v21, v4 offset:1088
	ds_write_b16_d16_hi v21, v4 offset:1360
	ds_write_b16 v21, v5 offset:1632
	ds_write_b16_d16_hi v21, v5 offset:1904
	v_and_b32_e32 v2, -8, v0
	v_ashrrev_i32_e32 v3, 31, v2
	v_lshl_add_u64 v[4:5], v[2:3], 1, v[14:15]
	global_load_dwordx4 v[10:13], v[4:5], off offset:3072
	v_mul_lo_u32 v0, v2, s65
	v_add3_u32 v22, 0, v0, v9
	v_add_u32_e32 v0, 0x600, v8
	v_ashrrev_i32_e32 v0, 4, v0
	s_waitcnt vmcnt(0)
	ds_write_b16 v22, v10
	ds_write_b16_d16_hi v22, v10 offset:272
	ds_write_b16 v22, v11 offset:544
	ds_write_b16_d16_hi v22, v11 offset:816
	ds_write_b16 v22, v12 offset:1088
	ds_write_b16_d16_hi v22, v12 offset:1360
	ds_write_b16 v22, v13 offset:1632
	ds_write_b16_d16_hi v22, v13 offset:1904
	v_and_b32_e32 v10, -8, v0
	v_ashrrev_i32_e32 v11, 31, v10
	v_lshl_add_u64 v[2:3], v[10:11], 1, v[14:15]
	v_mul_lo_u32 v0, v10, s65
	global_load_dwordx4 v[10:13], v[2:3], off offset:3072
	v_add3_u32 v9, 0, v0, v9
	v_bitop3_b32 v0, v8, s22, v8 bitop3:0xc
	v_cvt_f32_ubyte0_e32 v0, v0
	v_mul_f32_e32 v0, v17, v0
	v_exp_f32_e32 v0, v0
	v_bfi_b32 v17, -16, s20, v8
	s_mov_b32 s20, 0x30600000
	s_waitcnt vmcnt(0)
	ds_write_b16 v9, v10
	ds_write_b16_d16_hi v9, v10 offset:272
	ds_write_b16 v9, v11 offset:544
	ds_write_b16_d16_hi v9, v11 offset:816
	ds_write_b16 v9, v12 offset:1088
	ds_write_b16_d16_hi v9, v12 offset:1360
	ds_write_b16 v9, v13 offset:1632
	ds_write_b16_d16_hi v9, v13 offset:1904
	global_load_dwordx4 v[10:13], v[18:19], off offset:1536
	s_waitcnt vmcnt(0)
	v_lshlrev_b32_e32 v14, 16, v10
	v_and_b32_e32 v15, 0xffff0000, v10
	v_pk_mul_f32 v[14:15], v[0:1], v[14:15] op_sel_hi:[0,1]
	v_cvt_pk_bf16_f32 v10, v14, v15
	ds_write_b16 v20, v10 offset:34816
	ds_write_b16_d16_hi v20, v10 offset:35088
	v_lshlrev_b32_e32 v10, 16, v11
	v_and_b32_e32 v11, 0xffff0000, v11
	v_pk_mul_f32 v[10:11], v[0:1], v[10:11] op_sel_hi:[0,1]
	v_cvt_pk_bf16_f32 v10, v10, v11
	ds_write_b16 v20, v10 offset:35360
	ds_write_b16_d16_hi v20, v10 offset:35632
	v_lshlrev_b32_e32 v10, 16, v12
	v_and_b32_e32 v11, 0xffff0000, v12
	v_pk_mul_f32 v[10:11], v[0:1], v[10:11] op_sel_hi:[0,1]
	v_cvt_pk_bf16_f32 v10, v10, v11
	ds_write_b16 v20, v10 offset:35904
	ds_write_b16_d16_hi v20, v10 offset:36176
	v_lshlrev_b32_e32 v10, 16, v13
	v_and_b32_e32 v11, 0xffff0000, v13
	v_pk_mul_f32 v[10:11], v[0:1], v[10:11] op_sel_hi:[0,1]
	v_cvt_pk_bf16_f32 v10, v10, v11
	ds_write_b16 v20, v10 offset:36448
	ds_write_b16_d16_hi v20, v10 offset:36720
	global_load_dwordx4 v[10:13], v[6:7], off offset:1536
	s_waitcnt vmcnt(0)
; #define LAS __attribute__((address_space(3)))
; __device__ __forceinline__ unsigned pk2(float lo, float hi) { return pg8::cvt_pk_bf16(lo, hi); }
; __device__ __forceinline__ float fexp2(float x) { return __builtin_amdgcn_exp2f(x); }
; #define ZERO8(a) do { _Pragma("unroll") for (int t_ = 0; t_ < 8; ++t_) a[t_] = (f32x4){0.f, 0.f, 0.f, 0.f}; } while (0)
; template <bool SC> __device__ __forceinline__ void stage_tr(LAS bfu* dst, const bfu* src, int pitch, int tid, float lg) {
; #pragma unroll
;     for (int i = 0; i < 4; ++i) { const int id = tid + NTHR * i, c = id & 127, ch = id >> 7; const v4u v = *(const v4u*)(src + (size_t)c * pitch + ch * 8);
;         const float sc = SC ? fexp2(lg * (float)(127 - c)) : 1.f;
; #pragma unroll
;         for (int j = 0; j < 4; ++j) { unsigned w = v[j];
;             if (SC) w = pk2(bflo(w) * sc, bfhi(w) * sc);
;             dst[(ch * 8 + 2 * j) * TS + c] = (bfu)(w & 0xffffu); dst[(ch * 8 + 2 * j + 1) * TS + c] = (bfu)(w >> 16); } }
; }
; __device__ __forceinline__ void kv_unit(LAS unsigned char* lds, const bfu* PROJ, float* KVT, int u) {
;     ...
;     __syncthreads();
;     const int fr = lane & 15, fq = lane >> 4, m0 = wid * 16; f32x4 acc[8]; ZERO8(acc);
	v_lshlrev_b32_e32 v6, 16, v10
	v_and_b32_e32 v7, 0xffff0000, v10
	v_pk_mul_f32 v[6:7], v[0:1], v[6:7] op_sel_hi:[0,1]
	v_cvt_pk_bf16_f32 v6, v6, v7
	ds_write_b16 v21, v6 offset:34816
	ds_write_b16_d16_hi v21, v6 offset:35088
	v_lshlrev_b32_e32 v6, 16, v11
	v_and_b32_e32 v7, 0xffff0000, v11
	v_pk_mul_f32 v[6:7], v[0:1], v[6:7] op_sel_hi:[0,1]
	v_cvt_pk_bf16_f32 v6, v6, v7
	ds_write_b16 v21, v6 offset:35360
	ds_write_b16_d16_hi v21, v6 offset:35632
	v_lshlrev_b32_e32 v6, 16, v12
	v_and_b32_e32 v7, 0xffff0000, v12
	v_pk_mul_f32 v[6:7], v[0:1], v[6:7] op_sel_hi:[0,1]
	v_cvt_pk_bf16_f32 v6, v6, v7
	ds_write_b16 v21, v6 offset:35904
	ds_write_b16_d16_hi v21, v6 offset:36176
	v_lshlrev_b32_e32 v6, 16, v13
	v_and_b32_e32 v7, 0xffff0000, v13
	v_pk_mul_f32 v[6:7], v[0:1], v[6:7] op_sel_hi:[0,1]
	v_cvt_pk_bf16_f32 v6, v6, v7
	ds_write_b16 v21, v6 offset:36448
	ds_write_b16_d16_hi v21, v6 offset:36720
	global_load_dwordx4 v[4:7], v[4:5], off offset:1536
	s_waitcnt vmcnt(0)
	v_lshlrev_b32_e32 v10, 16, v4
	v_and_b32_e32 v11, 0xffff0000, v4
	v_pk_mul_f32 v[10:11], v[0:1], v[10:11] op_sel_hi:[0,1]
	v_cvt_pk_bf16_f32 v4, v10, v11
	ds_write_b16 v22, v4 offset:34816
	ds_write_b16_d16_hi v22, v4 offset:35088
	v_lshlrev_b32_e32 v4, 16, v5
	v_and_b32_e32 v5, 0xffff0000, v5
	v_pk_mul_f32 v[4:5], v[0:1], v[4:5] op_sel_hi:[0,1]
	v_cvt_pk_bf16_f32 v4, v4, v5
	ds_write_b16 v22, v4 offset:35360
	ds_write_b16_d16_hi v22, v4 offset:35632
	v_lshlrev_b32_e32 v4, 16, v6
	v_and_b32_e32 v5, 0xffff0000, v6
	v_pk_mul_f32 v[4:5], v[0:1], v[4:5] op_sel_hi:[0,1]
	v_cvt_pk_bf16_f32 v4, v4, v5
	ds_write_b16 v22, v4 offset:35904
	ds_write_b16_d16_hi v22, v4 offset:36176
	v_lshlrev_b32_e32 v4, 16, v7
	v_and_b32_e32 v5, 0xffff0000, v7
	v_pk_mul_f32 v[4:5], v[0:1], v[4:5] op_sel_hi:[0,1]
	v_cvt_pk_bf16_f32 v4, v4, v5
	ds_write_b16 v22, v4 offset:36448
	ds_write_b16_d16_hi v22, v4 offset:36720
	global_load_dwordx4 v[2:5], v[2:3], off offset:1536
	s_waitcnt vmcnt(0)
	v_lshlrev_b32_e32 v6, 16, v2
	v_and_b32_e32 v7, 0xffff0000, v2
	v_pk_mul_f32 v[6:7], v[0:1], v[6:7] op_sel_hi:[0,1]
	v_cvt_pk_bf16_f32 v2, v6, v7
	ds_write_b16 v9, v2 offset:34816
	ds_write_b16_d16_hi v9, v2 offset:35088
	v_lshlrev_b32_e32 v2, 16, v3
	v_and_b32_e32 v3, 0xffff0000, v3
	v_pk_mul_f32 v[2:3], v[0:1], v[2:3] op_sel_hi:[0,1]
	v_cvt_pk_bf16_f32 v2, v2, v3
	ds_write_b16 v9, v2 offset:35360
	ds_write_b16_d16_hi v9, v2 offset:35632
	v_lshlrev_b32_e32 v2, 16, v4
	v_and_b32_e32 v3, 0xffff0000, v4
	v_pk_mul_f32 v[2:3], v[0:1], v[2:3] op_sel_hi:[0,1]
	v_cvt_pk_bf16_f32 v2, v2, v3
	ds_write_b16 v9, v2 offset:35904
	ds_write_b16_d16_hi v9, v2 offset:36176
	v_lshlrev_b32_e32 v2, 16, v5
	v_and_b32_e32 v3, 0xffff0000, v5
	v_pk_mul_f32 v[2:3], v[0:1], v[2:3] op_sel_hi:[0,1]
	v_cvt_pk_bf16_f32 v0, v2, v3
	ds_write_b16 v9, v0 offset:36448
	ds_write_b16_d16_hi v9, v0 offset:36720
	v_and_b32_e32 v0, 48, v8
	v_and_b32_e32 v9, 15, v8
	v_add_u32_e32 v8, 0, v0
	v_mad_u64_u32 v[2:3], s[22:23], v17, s65, v[8:9]
	v_mad_u32_u24 v3, v9, s65, v8
	s_waitcnt lgkmcnt(0)
	s_barrier
; __device__ __forceinline__ void st_sc1_u2(void* p, unsigned lo, unsigned hi) { __hip_atomic_store((GAS unsigned long long*)p, ((unsigned long long)hi << 32) | (unsigned long long)lo, __ATOMIC_RELAXED, __HIP_MEMORY_SCOPE_AGENT); }
; __device__ __forceinline__ void st_sc1_x4(float* p, f32x4 v) { st_sc1_u2(p, __float_as_uint(v[0]), __float_as_uint(v[1])); st_sc1_u2(p + 2, __float_as_uint(v[2]), __float_as_uint(v[3])); }
; __device__ __forceinline__ void publish(unsigned* word) {
;     asm volatile("s_waitcnt vmcnt(0)" ::: "memory"); __syncthreads();
;     if (threadIdx.x == 0) __hip_atomic_fetch_add(word, 1u, __ATOMIC_RELAXED, __HIP_MEMORY_SCOPE_AGENT);
; __device__ __forceinline__ void kv_unit(LAS unsigned char* lds, const bfu* PROJ, float* KVT, int u) {
;     ...
;     wave_mma(acc, Vt, Kt, m0, fr, fq);
;     float* o = KVT + (size_t)u * 16384 + (m0 + fr) * 128 + 4 * fq;
; #pragma unroll
;     for (int t = 0; t < 8; ++t) st_sc1_x4(o + 16 * t, acc[t]);
	ds_read_b128 v[4:7], v2
	ds_read_b128 v[8:11], v3 offset:34816
	ds_read_b128 v[12:15], v3 offset:39168
	ds_read_b128 v[18:21], v3 offset:43520
	ds_read_b128 v[22:25], v3 offset:47872
	ds_read_b128 v[26:29], v3 offset:52224
	ds_read_b128 v[30:33], v3 offset:56576
	ds_read_b128 v[34:37], v3 offset:60928
	ds_read_b128 v[38:41], v3 offset:65280
	s_waitcnt lgkmcnt(7)
	v_mfma_f32_16x16x32_bf16 v[8:11], v[8:11], v[4:7], 0
	s_lshl_b64 s[22:23], s[40:41], 16
	s_add_u32 s22, s46, s22
	s_addc_u32 s23, s47, s23
	s_waitcnt lgkmcnt(6)
	v_mfma_f32_16x16x32_bf16 v[12:15], v[12:15], v[4:7], 0
	s_waitcnt lgkmcnt(5)
	v_mfma_f32_16x16x32_bf16 v[18:21], v[18:21], v[4:7], 0
	s_waitcnt lgkmcnt(4)
	v_mfma_f32_16x16x32_bf16 v[22:25], v[22:25], v[4:7], 0
	s_waitcnt lgkmcnt(3)
	v_mfma_f32_16x16x32_bf16 v[26:29], v[26:29], v[4:7], 0
	s_waitcnt lgkmcnt(2)
	v_mfma_f32_16x16x32_bf16 v[30:33], v[30:33], v[4:7], 0
	s_waitcnt lgkmcnt(1)
	v_mfma_f32_16x16x32_bf16 v[34:37], v[34:37], v[4:7], 0
	s_waitcnt lgkmcnt(0)
	v_mfma_f32_16x16x32_bf16 v[4:7], v[38:41], v[4:7], 0
	ds_read_b128 v[38:41], v2 offset:64
	ds_read_b128 v[42:45], v3 offset:34880
	s_waitcnt lgkmcnt(0)
	v_mfma_f32_16x16x32_bf16 v[8:11], v[42:45], v[38:41], v[8:11]
	ds_read_b128 v[42:45], v3 offset:39232
	s_waitcnt lgkmcnt(0)
	v_mfma_f32_16x16x32_bf16 v[12:15], v[42:45], v[38:41], v[12:15]
	ds_read_b128 v[42:45], v3 offset:43584
	s_waitcnt lgkmcnt(0)
	v_mfma_f32_16x16x32_bf16 v[18:21], v[42:45], v[38:41], v[18:21]
	ds_read_b128 v[42:45], v3 offset:47936
	s_waitcnt lgkmcnt(0)
	v_mfma_f32_16x16x32_bf16 v[22:25], v[42:45], v[38:41], v[22:25]
	ds_read_b128 v[42:45], v3 offset:52288
	s_waitcnt lgkmcnt(0)
	v_mfma_f32_16x16x32_bf16 v[26:29], v[42:45], v[38:41], v[26:29]
	ds_read_b128 v[42:45], v3 offset:56640
	s_waitcnt lgkmcnt(0)
	v_mfma_f32_16x16x32_bf16 v[30:33], v[42:45], v[38:41], v[30:33]
	ds_read_b128 v[42:45], v3 offset:60992
	s_waitcnt lgkmcnt(0)
	v_mfma_f32_16x16x32_bf16 v[34:37], v[42:45], v[38:41], v[34:37]
	ds_read_b128 v[42:45], v3 offset:65344
	s_waitcnt lgkmcnt(0)
	v_mfma_f32_16x16x32_bf16 v[4:7], v[42:45], v[38:41], v[4:7]
	ds_read_b128 v[38:41], v2 offset:128
	ds_read_b128 v[42:45], v3 offset:34944
	s_waitcnt lgkmcnt(0)
	v_mfma_f32_16x16x32_bf16 v[8:11], v[42:45], v[38:41], v[8:11]
	ds_read_b128 v[42:45], v3 offset:39296
	s_waitcnt lgkmcnt(0)
	v_mfma_f32_16x16x32_bf16 v[12:15], v[42:45], v[38:41], v[12:15]
	ds_read_b128 v[42:45], v3 offset:43648
	s_waitcnt lgkmcnt(0)
	v_mfma_f32_16x16x32_bf16 v[18:21], v[42:45], v[38:41], v[18:21]
	ds_read_b128 v[42:45], v3 offset:48000
	s_waitcnt lgkmcnt(0)
	v_mfma_f32_16x16x32_bf16 v[22:25], v[42:45], v[38:41], v[22:25]
	ds_read_b128 v[42:45], v3 offset:52352
	s_waitcnt lgkmcnt(0)
	v_mfma_f32_16x16x32_bf16 v[26:29], v[42:45], v[38:41], v[26:29]
	ds_read_b128 v[42:45], v3 offset:56704
	s_waitcnt lgkmcnt(0)
	v_mfma_f32_16x16x32_bf16 v[30:33], v[42:45], v[38:41], v[30:33]
	ds_read_b128 v[42:45], v3 offset:61056
	s_waitcnt lgkmcnt(0)
	v_mfma_f32_16x16x32_bf16 v[34:37], v[42:45], v[38:41], v[34:37]
	ds_read_b128 v[42:45], v3 offset:65408
	s_waitcnt lgkmcnt(0)
	v_mfma_f32_16x16x32_bf16 v[4:7], v[42:45], v[38:41], v[4:7]
	ds_read_b128 v[38:41], v2 offset:192
	ds_read_b128 v[42:45], v3 offset:35008
	s_waitcnt lgkmcnt(0)
	v_mfma_f32_16x16x32_bf16 v[8:11], v[42:45], v[38:41], v[8:11]
	ds_read_b128 v[42:45], v3 offset:39360
	s_waitcnt lgkmcnt(0)
	v_mfma_f32_16x16x32_bf16 v[12:15], v[42:45], v[38:41], v[12:15]
	ds_read_b128 v[42:45], v3 offset:43712
	s_waitcnt lgkmcnt(0)
	v_mfma_f32_16x16x32_bf16 v[18:21], v[42:45], v[38:41], v[18:21]
	ds_read_b128 v[42:45], v3 offset:48064
	s_waitcnt lgkmcnt(0)
	v_mfma_f32_16x16x32_bf16 v[22:25], v[42:45], v[38:41], v[22:25]
	ds_read_b128 v[42:45], v3 offset:52416
	s_waitcnt lgkmcnt(0)
	v_mfma_f32_16x16x32_bf16 v[26:29], v[42:45], v[38:41], v[26:29]
	ds_read_b128 v[42:45], v3 offset:56768
	s_waitcnt lgkmcnt(0)
	v_mfma_f32_16x16x32_bf16 v[30:33], v[42:45], v[38:41], v[30:33]
	ds_read_b128 v[42:45], v3 offset:61120
	s_waitcnt lgkmcnt(0)
	v_mfma_f32_16x16x32_bf16 v[34:37], v[42:45], v[38:41], v[34:37]
	ds_read_b128 v[42:45], v3 offset:65472
	s_waitcnt lgkmcnt(0)
	v_mfma_f32_16x16x32_bf16 v[2:5], v[42:45], v[38:41], v[4:7]
	s_nop 2
	v_lshlrev_b32_e32 v6, 7, v17
	v_ashrrev_i32_e32 v7, 31, v6
	v_lshl_add_u64 v[6:7], v[6:7], 2, s[22:23]
	v_lshl_add_u64 v[6:7], v[6:7], 0, v[0:1]
	s_mov_b64 s[22:23], 0x30600000
	v_lshl_add_u64 v[38:39], v[6:7], 0, s[22:23]
	v_add_co_u32_e32 v6, vcc, s20, v6
	s_nop 1
	v_addc_co_u32_e32 v7, vcc, 0, v7, vcc
	global_store_dwordx4 v[38:39], v[8:11], off sc1
	global_store_dwordx4 v[38:39], v[12:15], off offset:64 sc1
	global_store_dwordx4 v[38:39], v[18:21], off offset:128 sc1
	global_store_dwordx4 v[38:39], v[22:25], off offset:192 sc1
	global_store_dwordx4 v[38:39], v[26:29], off offset:256 sc1
	global_store_dwordx4 v[38:39], v[30:33], off offset:320 sc1
	global_store_dwordx4 v[38:39], v[34:37], off offset:384 sc1
	global_store_dwordx4 v[38:39], v[2:5], off offset:448 sc1
	s_waitcnt vmcnt(0)
	s_barrier
	s_and_saveexec_b64 s[40:41], s[74:75]
	s_ashr_i32 s45, s44, 31
	s_lshl_b64 s[22:23], s[44:45], 2
	s_add_u32 s20, s4, s22
	s_addc_u32 s22, s5, s23
	s_add_u32 s34, s20, 0x200
	s_addc_u32 s35, s22, 0
	s_or_b64 s[42:43], s[42:43], exec
	s_or_b64 exec, exec, s[40:41]
